# GDN chain sections B/C (R = beta*(v - exp(gc)*(k@S))): LDS reads issued one 16-token tile ahead of the arithmetic with counted waits
# baseline (speedup 1.0000x reference)
; #define LAS __attribute__((address_space(3)))
; __device__ __forceinline__ unsigned pk2(float lo, float hi) { const f32v2_t f = {lo, hi}; const bf16v2_t b = __builtin_convertvector(f, bf16v2_t); return __builtin_bit_cast(unsigned, b); }
; #define WAVE_SYNC() do { asm volatile("s_waitcnt lgkmcnt(0)" ::: "memory"); __builtin_amdgcn_wave_barrier(); asm volatile("" ::: "memory"); } while (0)
; #define MFMA16(a, b, c) __builtin_amdgcn_mfma_f32_16x16x32_bf16((a), (b), (c), 0, 0, 0)
; template <int MODE>
; __device__ NOINL void chain_item(const LAS Params* lp, int l, int item, bool ctx_out, LAS unsigned char* lds) {
;     ...
;         for (int dk = 0; dk < NDK; ++dk) { u32x2 pk; pk.x = pk2(Sacc[dk][0], Sacc[dk][1]); pk.y = pk2(Sacc[dk][2], Sacc[dk][3]); *(LAS u32x2*)(ST + fr * 136 + 16 * dk + 4 * fq) = pk; }
;         WAVE_SYNC();
;         f32x4 qs[4], ksm[4];
; #pragma unroll
;         for (int ct = 0; ct < 4; ++ct) { qs[ct] = (f32x4){0.f, 0.f, 0.f, 0.f}; ksm[ct] = (f32x4){0.f, 0.f, 0.f, 0.f}; }
; #pragma unroll
;         for (int ks = 0; ks < NKS; ++ks) {
;             const bf16x8 Bf = *(const LAS bf16x8*)(ST + fr * 136 + ks * 32 + fq * 8);
; #pragma unroll
;             for (int ct = 0; ct < 4; ++ct) {
;                 const bf16x8 Aq = *(const LAS bf16x8*)(Qs + (16 * ct + fr) * 136 + kcol + ks * 32 + fq * 8);
;                 qs[ct] = MFMA16(Aq, Bf, qs[ct]);
;                 if (MODE == 0) { const bf16x8 Ak = *(const LAS bf16x8*)(Ks + (16 * ct + fr) * 136 + ks * 32 + fq * 8); ksm[ct] = MFMA16(Ak, Bf, ksm[ct]); }
;             }
;         }
.LBB0_1141:
	s_or_b64 exec, exec, s[62:63]
	ds_write_b16 v178, v68
	v_cvt_pk_bf16_f32 v68, v28, v29
	v_cvt_pk_bf16_f32 v69, v30, v31
	v_cvt_pk_bf16_f32 v70, v40, v41
	v_cvt_pk_bf16_f32 v71, v42, v43
	ds_write2_b64 v113, v[68:69], v[70:71] offset1:4
	v_cvt_pk_bf16_f32 v68, v32, v33
	v_cvt_pk_bf16_f32 v69, v34, v35
	v_cvt_pk_bf16_f32 v70, v36, v37
	v_cvt_pk_bf16_f32 v71, v38, v39
	ds_write2_b64 v113, v[68:69], v[70:71] offset0:8 offset1:12
	v_cvt_pk_bf16_f32 v68, v56, v57
	v_cvt_pk_bf16_f32 v69, v58, v59
	v_cvt_pk_bf16_f32 v70, v52, v53
	v_cvt_pk_bf16_f32 v71, v54, v55
	ds_write2_b64 v113, v[68:69], v[70:71] offset0:16 offset1:20
	v_cvt_pk_bf16_f32 v68, v44, v45
	v_cvt_pk_bf16_f32 v69, v46, v47
	v_cvt_pk_bf16_f32 v70, v48, v49
	v_cvt_pk_bf16_f32 v71, v50, v51
	ds_write2_b64 v113, v[68:69], v[70:71] offset0:24 offset1:28
	s_waitcnt lgkmcnt(0)
	v_add_u32_e32 v119, v113, v154
	ds_read_b128 v[84:87], v119
	ds_read_b128 v[100:103], v179
	ds_read_b128 v[104:107], v179 offset:17408
	ds_read_b128 v[194:197], v179 offset:4352
	ds_read_b128 v[236:239], v179 offset:21760
	ds_read_b128 v[240:243], v179 offset:8704
	ds_read_b128 v[244:247], v179 offset:26112
	ds_read_b128 v[248:251], v179 offset:13056
	v_add_u32_e32 v121, 0x25500, v110
	s_waitcnt lgkmcnt(6)
	v_mfma_f32_16x16x32_bf16 v[96:99], v[100:103], v[84:87], 0
	ds_read_b128 v[100:103], v179 offset:30464
	ds_read_b128 v[88:91], v119 offset:64
	s_add_i32 s5, s4, 4
	s_waitcnt lgkmcnt(7)
	v_mfma_f32_16x16x32_bf16 v[198:201], v[104:107], v[84:87], 0
	ds_read_b128 v[104:107], v179 offset:64
	s_and_b64 s[20:21], vcc, exec
	s_waitcnt lgkmcnt(7)
	v_mfma_f32_16x16x32_bf16 v[92:95], v[194:197], v[84:87], 0
	ds_read_b128 v[194:197], v179 offset:17472
	s_cselect_b32 s5, s1, s5
	s_waitcnt lgkmcnt(7)
	v_mfma_f32_16x16x32_bf16 v[232:235], v[236:239], v[84:87], 0
	ds_read_b128 v[236:239], v179 offset:4416
	s_add_i32 s22, s4, 40
	s_waitcnt lgkmcnt(7)
	v_mfma_f32_16x16x32_bf16 v[80:83], v[240:243], v[84:87], 0
	ds_read_b128 v[240:243], v179 offset:21824
	s_and_b64 s[20:21], vcc, exec
	s_waitcnt lgkmcnt(7)
	v_mfma_f32_16x16x32_bf16 v[72:75], v[244:247], v[84:87], 0
	ds_read_b128 v[244:247], v179 offset:8768
	s_cselect_b32 s20, s1, s22
	s_waitcnt lgkmcnt(7)
	v_mfma_f32_16x16x32_bf16 v[76:79], v[248:251], v[84:87], 0
	ds_read_b128 v[248:251], v179 offset:26176
	s_cmp_lt_u32 s1, 4
	s_waitcnt lgkmcnt(7)
	v_mfma_f32_16x16x32_bf16 v[68:71], v[100:103], v[84:87], 0
	ds_read_b128 v[100:103], v179 offset:13120
	s_cselect_b32 s1, s5, s20
	s_waitcnt lgkmcnt(6)
	v_mfma_f32_16x16x32_bf16 v[96:99], v[104:107], v[88:91], v[96:99]
	ds_read_b128 v[104:107], v179 offset:30528
	ds_read_b128 v[84:87], v119 offset:128
	s_lshl_b32 s5, s1, 6
	s_waitcnt lgkmcnt(7)
	v_mfma_f32_16x16x32_bf16 v[198:201], v[194:197], v[88:91], v[198:201]
	ds_read_b128 v[194:197], v179 offset:128
	s_add_i32 s20, s18, s5
	s_waitcnt lgkmcnt(7)
	v_mfma_f32_16x16x32_bf16 v[92:95], v[236:239], v[88:91], v[92:95]
	ds_read_b128 v[236:239], v179 offset:17536
	s_or_b32 s5, s5, s38
	s_waitcnt lgkmcnt(7)
	v_mfma_f32_16x16x32_bf16 v[232:235], v[240:243], v[88:91], v[232:235]
	ds_read_b128 v[240:243], v179 offset:4480
	s_cmp_lt_u32 s1, 4
	s_waitcnt lgkmcnt(7)
	v_mfma_f32_16x16x32_bf16 v[80:83], v[244:247], v[88:91], v[80:83]
	ds_read_b128 v[244:247], v179 offset:21888
	s_cselect_b32 s1, s5, s20
	s_waitcnt lgkmcnt(7)
	v_mfma_f32_16x16x32_bf16 v[72:75], v[248:251], v[88:91], v[72:75]
	ds_read_b128 v[248:251], v179 offset:8832
	s_mul_hi_i32 s21, s1, s19
	s_waitcnt lgkmcnt(7)
	v_mfma_f32_16x16x32_bf16 v[76:79], v[100:103], v[88:91], v[76:79]
	ds_read_b128 v[100:103], v179 offset:26240
	s_mul_i32 s20, s1, s19
	s_waitcnt lgkmcnt(7)
	v_mfma_f32_16x16x32_bf16 v[68:71], v[104:107], v[88:91], v[68:71]
	ds_read_b128 v[104:107], v179 offset:13184
	v_mov_b32_e32 v123, v1
	s_waitcnt lgkmcnt(6)
	v_mfma_f32_16x16x32_bf16 v[96:99], v[194:197], v[84:87], v[96:99]
	ds_read_b128 v[194:197], v179 offset:30592
	ds_read_b128 v[88:91], v119 offset:192
	v_add_u32_e32 v119, s34, v155
	v_mov_b32_e32 v125, v1
	s_waitcnt lgkmcnt(7)
	v_mfma_f32_16x16x32_bf16 v[198:201], v[236:239], v[84:87], v[198:201]
	ds_read_b128 v[236:239], v179 offset:192
	v_mov_b32_e32 v127, v1
	s_waitcnt lgkmcnt(7)
	v_mfma_f32_16x16x32_bf16 v[92:95], v[240:243], v[84:87], v[92:95]
	ds_read_b128 v[240:243], v179 offset:17600
	v_mov_b32_e32 v129, v1
	s_waitcnt lgkmcnt(7)
	v_mfma_f32_16x16x32_bf16 v[232:235], v[244:247], v[84:87], v[232:235]
	ds_read_b128 v[244:247], v179 offset:4544
	v_mov_b32_e32 v131, v1
	s_waitcnt lgkmcnt(7)
	v_mfma_f32_16x16x32_bf16 v[80:83], v[248:251], v[84:87], v[80:83]
	ds_read_b128 v[248:251], v179 offset:21952
	v_mov_b32_e32 v133, v1
	s_waitcnt lgkmcnt(7)
	v_mfma_f32_16x16x32_bf16 v[72:75], v[100:103], v[84:87], v[72:75]
	ds_read_b128 v[100:103], v179 offset:8896
	v_mov_b32_e32 v135, v1
	s_waitcnt lgkmcnt(7)
	v_mfma_f32_16x16x32_bf16 v[76:79], v[104:107], v[84:87], v[76:79]
	ds_read_b128 v[104:107], v179 offset:26304
	v_mov_b32_e32 v137, v1
	s_waitcnt lgkmcnt(7)
	v_mfma_f32_16x16x32_bf16 v[68:71], v[194:197], v[84:87], v[68:71]
	ds_read_b128 v[194:197], v179 offset:13248
	v_mov_b32_e32 v139, v1
	s_waitcnt lgkmcnt(6)
	v_mfma_f32_16x16x32_bf16 v[96:99], v[236:239], v[88:91], v[96:99]
	ds_read_b128 v[236:239], v179 offset:30656
	v_mov_b32_e32 v141, v1
	s_waitcnt lgkmcnt(6)
	v_mfma_f32_16x16x32_bf16 v[198:201], v[240:243], v[88:91], v[198:201]
	v_mov_b32_e32 v143, v1
	s_waitcnt lgkmcnt(5)
	v_mfma_f32_16x16x32_bf16 v[92:95], v[244:247], v[88:91], v[92:95]
	v_mov_b32_e32 v145, v1
	s_waitcnt lgkmcnt(4)
	v_mfma_f32_16x16x32_bf16 v[232:235], v[248:251], v[88:91], v[232:235]
	v_mov_b32_e32 v147, v1
	s_waitcnt lgkmcnt(3)
; #define LAS __attribute__((address_space(3)))
; __device__ __forceinline__ unsigned pk2(float lo, float hi) { const f32v2_t f = {lo, hi}; const bf16v2_t b = __builtin_convertvector(f, bf16v2_t); return __builtin_bit_cast(unsigned, b); }
; __device__ __forceinline__ float bflo(unsigned u) { return __uint_as_float(u << 16); }
; __device__ __forceinline__ float bfhi(unsigned u) { return __uint_as_float(u & 0xFFFF0000u); }
; template <int MODE>
; __device__ NOINL void chain_item(const LAS Params* lp, int l, int item, bool ctx_out, LAS unsigned char* lds) {
;     ...
;         float eg[4][4];
; #pragma unroll
;         for (int ct = 0; ct < 4; ++ct)
; #pragma unroll
;             for (int j = 0; j < 4; ++j) { const int c = 16 * ct + 4 * fq + j; eg[ct][j] = MODE == 0 ? gcs[128 + c] : __expf((float)(c + 1) * lg); }
;         bf16x8 Bv[2];
;         if (MODE == 0) {
; #pragma unroll
;             for (int ct = 0; ct < 4; ++ct) {
;                 const u32x2 vv = *(const LAS u32x2*)(VT + (dvrow + fr) * 72 + (((2 * ct + (fq >> 1)) ^ vkey) << 3) + 4 * (fq & 1));
;                 const float v4[4] = {bflo(vv.x), bfhi(vv.x), bflo(vv.y), bfhi(vv.y)};
;                 float r[4];
; #pragma unroll
;                 for (int j = 0; j < 4; ++j) r[j] = bts[16 * ct + 4 * fq + j] * (v4[j] - eg[ct][j] * ksm[ct][j]);
;                 u32x2 pk; pk.x = pk2(r[0], r[1]); pk.y = pk2(r[2], r[3]);
;                 *(LAS u32x2*)(RP + fr * 72 + 16 * ct + 4 * fq) = pk;
;             }
;             WAVE_SYNC();
;             bf16x8 Br[2];
;             Br[0] = *(const LAS bf16x8*)(RP + fr * 72 + fq * 8); Br[1] = *(const LAS bf16x8*)(RP + fr * 72 + 32 + fq * 8);
;             f32x4 vn[4];
; #pragma unroll
;             for (int ct = 0; ct < 4; ++ct) {
;                 vn[ct] = (f32x4){0.f, 0.f, 0.f, 0.f};
; #pragma unroll
;                 for (int ks = 0; ks < 2; ++ks) { const bf16x8 A = *(const LAS bf16x8*)(TT + (16 * ct + fr) * 72 + ks * 32 + fq * 8); vn[ct] = MFMA16(A, Br[ks], vn[ct]); }
;             }
;             WAVE_SYNC();
; #pragma unroll
;             for (int ct = 0; ct < 4; ++ct) { u32x2 pk; pk.x = pk2(vn[ct][0], vn[ct][1]); pk.y = pk2(vn[ct][2], vn[ct][3]); *(LAS u32x2*)(RP + fr * 72 + 16 * ct + 4 * fq) = pk; }
;             WAVE_SYNC();
;             Bv[0] = *(const LAS bf16x8*)(RP + fr * 72 + fq * 8); Bv[1] = *(const LAS bf16x8*)(RP + fr * 72 + 32 + fq * 8);
	v_mfma_f32_16x16x32_bf16 v[80:83], v[100:103], v[88:91], v[80:83]
	s_add_i32 s4, s4, -1
	s_waitcnt lgkmcnt(2)
	v_mfma_f32_16x16x32_bf16 v[72:75], v[104:107], v[88:91], v[72:75]
	s_cmp_lg_u32 s0, 36
	s_waitcnt lgkmcnt(1)
	v_mfma_f32_16x16x32_bf16 v[76:79], v[194:197], v[88:91], v[76:79]
	s_mov_b32 s1, s0
	s_waitcnt lgkmcnt(0)
	v_mfma_f32_16x16x32_bf16 v[68:71], v[236:239], v[88:91], v[68:71]
	ds_read_b128 v[104:107], v119 offset:512
	ds_read_b64 v[248:249], v186 offset:53248
	ds_read_b128 v[236:239], v121
	ds_read_b128 v[100:103], v119 offset:576
	ds_read_b64 v[250:251], v187 offset:53248
	ds_read_b128 v[240:243], v121 offset:64
	ds_read_b128 v[88:91], v119 offset:640
	ds_read_b128 v[84:87], v119 offset:704
	v_add_u32_e32 v119, v158, v154
	s_waitcnt lgkmcnt(6)
	v_lshlrev_b32_e32 v244, 16, v248
	v_and_b32_e32 v245, 0xffff0000, v248
	v_lshlrev_b32_e32 v246, 16, v249
	v_and_b32_e32 v247, 0xffff0000, v249
	v_pk_fma_f32 v[198:199], v[198:199], v[104:105], v[244:245] neg_lo:[1,0,0] neg_hi:[1,0,0]
	v_pk_fma_f32 v[200:201], v[200:201], v[106:107], v[246:247] neg_lo:[1,0,0] neg_hi:[1,0,0]
	s_waitcnt lgkmcnt(5)
	v_pk_mul_f32 v[198:199], v[236:237], v[198:199]
	v_pk_mul_f32 v[200:201], v[238:239], v[200:201]
	v_cvt_pk_bf16_f32 v198, v198, v199
	v_cvt_pk_bf16_f32 v199, v200, v201
	ds_write_b64 v158, v[198:199] offset:4352
	ds_read_b64 v[248:249], v188 offset:53248
	ds_read_b128 v[236:239], v121 offset:128
	s_waitcnt lgkmcnt(6)
	v_lshlrev_b32_e32 v194, 16, v250
	v_and_b32_e32 v195, 0xffff0000, v250
	v_lshlrev_b32_e32 v196, 16, v251
	v_and_b32_e32 v197, 0xffff0000, v251
	v_pk_fma_f32 v[232:233], v[232:233], v[100:101], v[194:195] neg_lo:[1,0,0] neg_hi:[1,0,0]
	v_pk_fma_f32 v[234:235], v[234:235], v[102:103], v[196:197] neg_lo:[1,0,0] neg_hi:[1,0,0]
	s_waitcnt lgkmcnt(5)
	v_pk_mul_f32 v[232:233], v[240:241], v[232:233]
	v_pk_mul_f32 v[234:235], v[242:243], v[234:235]
	v_cvt_pk_bf16_f32 v232, v232, v233
	v_cvt_pk_bf16_f32 v233, v234, v235
	ds_write_b64 v158, v[232:233] offset:4384
	ds_read_b64 v[250:251], v189 offset:53248
	ds_read_b128 v[240:243], v121 offset:192
	s_waitcnt lgkmcnt(4)
	v_lshlrev_b32_e32 v244, 16, v248
	v_and_b32_e32 v245, 0xffff0000, v248
	v_lshlrev_b32_e32 v246, 16, v249
	v_and_b32_e32 v247, 0xffff0000, v249
	v_pk_fma_f32 v[72:73], v[72:73], v[88:89], v[244:245] neg_lo:[1,0,0] neg_hi:[1,0,0]
	v_pk_fma_f32 v[74:75], v[74:75], v[90:91], v[246:247] neg_lo:[1,0,0] neg_hi:[1,0,0]
	s_waitcnt lgkmcnt(3)
	v_pk_mul_f32 v[72:73], v[236:237], v[72:73]
	v_pk_mul_f32 v[74:75], v[238:239], v[74:75]
	v_cvt_pk_bf16_f32 v72, v72, v73
	v_cvt_pk_bf16_f32 v73, v74, v75
	ds_write_b64 v158, v[72:73] offset:4416
	s_waitcnt lgkmcnt(2)
	v_lshlrev_b32_e32 v194, 16, v250
	v_and_b32_e32 v195, 0xffff0000, v250
	v_lshlrev_b32_e32 v196, 16, v251
	v_and_b32_e32 v197, 0xffff0000, v251
	v_pk_fma_f32 v[68:69], v[68:69], v[84:85], v[194:195] neg_lo:[1,0,0] neg_hi:[1,0,0]
	v_pk_fma_f32 v[70:71], v[70:71], v[86:87], v[196:197] neg_lo:[1,0,0] neg_hi:[1,0,0]
	s_waitcnt lgkmcnt(1)
	v_pk_mul_f32 v[68:69], v[240:241], v[68:69]
	v_pk_mul_f32 v[70:71], v[242:243], v[70:71]
	v_cvt_pk_bf16_f32 v68, v68, v69
	v_cvt_pk_bf16_f32 v69, v70, v71
	ds_write_b64 v158, v[68:69] offset:4448
	v_add_u32_e32 v121, v159, v157
	v_lshl_add_u64 v[148:149], s[20:21], 1, v[116:117]
	s_waitcnt lgkmcnt(0)
	ds_read_b128 v[68:71], v119 offset:4352
	ds_read_b128 v[72:75], v119 offset:4416
	ds_read_b128 v[194:197], v121
	ds_read_b128 v[198:201], v121 offset:64
	v_add_u32_e32 v121, v159, v180
	ds_read_b128 v[232:235], v121
	ds_read_b128 v[236:239], v121 offset:64
	ds_read_b128 v[240:243], v121 offset:2304
	ds_read_b128 v[244:247], v121 offset:2368
	ds_read_b128 v[248:251], v121 offset:4608
	s_waitcnt lgkmcnt(6)
	v_mfma_f32_16x16x32_bf16 v[194:197], v[194:197], v[68:71], 0
	s_waitcnt lgkmcnt(5)
	v_mfma_f32_16x16x32_bf16 v[194:197], v[198:201], v[72:75], v[194:197]
	ds_read_b128 v[198:201], v121 offset:4672
	v_add_u32_e32 v121, 0x1000, v158
	s_waitcnt lgkmcnt(5)
	v_mfma_f32_16x16x32_bf16 v[232:235], v[232:235], v[68:71], 0
	s_waitcnt lgkmcnt(4)
	v_mfma_f32_16x16x32_bf16 v[232:235], v[236:239], v[72:75], v[232:235]
	s_waitcnt lgkmcnt(3)
	v_mfma_f32_16x16x32_bf16 v[240:243], v[240:243], v[68:71], 0
	s_waitcnt lgkmcnt(2)
	v_mfma_f32_16x16x32_bf16 v[240:243], v[244:247], v[72:75], v[240:243]
	s_waitcnt lgkmcnt(1)
	v_mfma_f32_16x16x32_bf16 v[248:251], v[248:251], v[68:71], 0
	s_waitcnt lgkmcnt(0)
	v_mfma_f32_16x16x32_bf16 v[248:251], v[198:201], v[72:75], v[248:251]
	v_cvt_pk_bf16_f32 v72, v194, v195
	v_cvt_pk_bf16_f32 v73, v196, v197
	v_cvt_pk_bf16_f32 v74, v232, v233
	v_cvt_pk_bf16_f32 v75, v234, v235
	ds_write2_b64 v121, v[72:73], v[74:75] offset0:32 offset1:36
	v_cvt_pk_bf16_f32 v72, v240, v241
	v_cvt_pk_bf16_f32 v73, v242, v243
	s_nop 1
	v_cvt_pk_bf16_f32 v68, v248, v249
	v_cvt_pk_bf16_f32 v69, v250, v251
	ds_write2_b64 v121, v[72:73], v[68:69] offset0:40 offset1:44
	s_waitcnt lgkmcnt(0)
	s_barrier
; #define LAS __attribute__((address_space(3)))
; __device__ __forceinline__ bf16_t f2bf(float f) { return (bf16_t)(pk2(f, f) & 0xFFFFu); }
; #define MFMA16(a, b, c) __builtin_amdgcn_mfma_f32_16x16x32_bf16((a), (b), (c), 0, 0, 0)
; template <int MODE>
; __device__ NOINL void chain_item(const LAS Params* lp, int l, int item, bool ctx_out, LAS unsigned char* lds) {
;     ...
;             Bv[0] = *(const LAS bf16x8*)(RP + fr * 72 + fq * 8); Bv[1] = *(const LAS bf16x8*)(RP + fr * 72 + 32 + fq * 8);
;         } else {
;             Bv[0] = *(const LAS bf16x8*)(VT + (dvrow + fr) * 72 + ((fq ^ vkey) << 3)); Bv[1] = *(const LAS bf16x8*)(VT + (dvrow + fr) * 72 + (((4 + fq) ^ vkey) << 3));
;         }
;         {
;             typedef __attribute__((address_space(1))) bf16_t gbf16;
;             bf16_t* ob; int ldo;
;             if (MODE == 0) { if (dir == 0) { ob = p.hbuf + 256 + h * 128 + 16 * w; ldo = 1024; } else { ob = p.hyproj + h * 128 + 16 * w; ldo = 768; } }
;             else { if (dir == 0) { ob = p.hbuf + 768 + (h + hh) * 64 + 16 * (w & 3); ldo = 1024; } else { ob = p.hyproj + 512 + (h + hh) * 64 + 16 * (w & 3); ldo = 768; } }
; #pragma unroll
;             for (int ct = 0; ct < 4; ++ct) {
;                 f32x4 acc = {0.f, 0.f, 0.f, 0.f};
; #pragma unroll
;                 for (int ks = 0; ks < 2; ++ks) { const bf16x8 A = *(const LAS bf16x8*)(AT + hh * 4608 + (16 * ct + fr) * 72 + ks * 32 + fq * 8); acc = MFMA16(A, Bv[ks], acc); }
;                 gbf16* og = (gbf16*)ob + (size_t)row0 * ldo + fr;
; #pragma unroll
;                 for (int j = 0; j < 4; ++j) { const int c = 16 * ct + 4 * fq + j, tok = dir ? 63 - c : c; og[tok * ldo] = f2bf(eg[ct][j] * qs[ct][j] + acc[j]); }
;             }
;         }
;         {
;             const float gl = MODE == 0 ? gcs[128 + 63] : __expf(64.f * lg);
; #pragma unroll
;             for (int dk = 0; dk < NDK; ++dk) {
;                 Sacc[dk] = Sacc[dk] * gl;
; #pragma unroll
;                 for (int ks = 0; ks < 2; ++ks) { const bf16x8 A = *(const LAS bf16x8*)(KT + (kcol + 16 * dk + fr) * 72 + (((ks * 4 + fq) ^ (((kcol >> 4) + dk) & 7)) << 3)); Sacc[dk] = MFMA16(A, Bv[ks], Sacc[dk]); }
	ds_read_b128 v[72:75], v119 offset:4352
	ds_read_b128 v[68:71], v119 offset:4416
	v_add_u32_e32 v218, v160, v157
	v_add_u32_e32 v219, v160, v180
	v_mov_b32_e32 v119, v1
	v_mov_b32_e32 v121, v1
	ds_read_b128 v[194:197], v218
	ds_read_b128 v[232:235], v219
	ds_read_b128 v[244:247], v219 offset:2304
	ds_read_b128 v[236:239], v219 offset:4608
	ds_read_b128 v[198:201], v218 offset:64
	ds_read_b128 v[240:243], v219 offset:64
	ds_read_b128 v[248:251], v219 offset:2368
	s_waitcnt lgkmcnt(6)
	v_mfma_f32_16x16x32_bf16 v[194:197], v[194:197], v[72:75], 0
	s_waitcnt lgkmcnt(5)
	v_mfma_f32_16x16x32_bf16 v[232:235], v[232:235], v[72:75], 0
	s_waitcnt lgkmcnt(4)
	v_mfma_f32_16x16x32_bf16 v[244:247], v[244:247], v[72:75], 0
	s_waitcnt lgkmcnt(3)
	v_mfma_f32_16x16x32_bf16 v[236:239], v[236:239], v[72:75], 0
	s_waitcnt lgkmcnt(2)
	v_mfma_f32_16x16x32_bf16 v[194:197], v[198:201], v[68:71], v[194:197]
	ds_read_b128 v[198:201], v219 offset:4672
	s_waitcnt lgkmcnt(2)
	v_mfma_f32_16x16x32_bf16 v[232:235], v[240:243], v[68:71], v[232:235]
	s_waitcnt lgkmcnt(1)
	v_mfma_f32_16x16x32_bf16 v[244:247], v[248:251], v[68:71], v[244:247]
	s_waitcnt lgkmcnt(0)
	v_mfma_f32_16x16x32_bf16 v[236:239], v[198:201], v[68:71], v[236:239]
	v_lshl_add_u64 v[240:241], v[148:149], 0, v[0:1]
	v_lshl_add_u64 v[242:243], v[148:149], 0, v[118:119]
	v_lshl_add_u64 v[248:249], v[148:149], 0, v[120:121]
	v_lshl_add_u64 v[250:251], v[148:149], 0, v[122:123]
	s_nop 3
	v_fma_f32 v194, v96, v104, v194
	v_fma_f32 v195, v97, v105, v195
	v_fma_f32 v196, v98, v106, v196
	v_fma_f32 v197, v99, v107, v197
	v_cvt_pk_bf16_f32 v194, v194, v194
	v_cvt_pk_bf16_f32 v195, v195, v195
	v_cvt_pk_bf16_f32 v196, v196, v196
	v_cvt_pk_bf16_f32 v197, v197, v197
	global_store_short v[240:241], v194, off
	global_store_short v[242:243], v195, off
	global_store_short v[248:249], v196, off
	global_store_short v[250:251], v197, off
	v_lshl_add_u64 v[240:241], v[148:149], 0, v[124:125]
	v_lshl_add_u64 v[242:243], v[148:149], 0, v[126:127]
	v_lshl_add_u64 v[248:249], v[148:149], 0, v[128:129]
	v_lshl_add_u64 v[250:251], v[148:149], 0, v[130:131]
	v_fma_f32 v232, v92, v100, v232
	v_fma_f32 v233, v93, v101, v233
	v_fma_f32 v234, v94, v102, v234
	v_fma_f32 v235, v95, v103, v235
	v_cvt_pk_bf16_f32 v232, v232, v232
	v_cvt_pk_bf16_f32 v233, v233, v233
	v_cvt_pk_bf16_f32 v234, v234, v234
	v_cvt_pk_bf16_f32 v235, v235, v235
	global_store_short v[240:241], v232, off
	global_store_short v[242:243], v233, off
	global_store_short v[248:249], v234, off
	global_store_short v[250:251], v235, off
	v_lshl_add_u64 v[240:241], v[148:149], 0, v[132:133]
	v_lshl_add_u64 v[242:243], v[148:149], 0, v[134:135]
	v_lshl_add_u64 v[248:249], v[148:149], 0, v[136:137]
	v_lshl_add_u64 v[250:251], v[148:149], 0, v[138:139]
	v_fma_f32 v244, v80, v88, v244
	v_fma_f32 v245, v81, v89, v245
	v_fma_f32 v246, v82, v90, v246
	v_fma_f32 v247, v83, v91, v247
	v_cvt_pk_bf16_f32 v244, v244, v244
	v_cvt_pk_bf16_f32 v245, v245, v245
	v_cvt_pk_bf16_f32 v246, v246, v246
	v_cvt_pk_bf16_f32 v247, v247, v247
	global_store_short v[240:241], v244, off
	global_store_short v[242:243], v245, off
	global_store_short v[248:249], v246, off
	global_store_short v[250:251], v247, off
	v_lshl_add_u64 v[240:241], v[148:149], 0, v[140:141]
	v_lshl_add_u64 v[242:243], v[148:149], 0, v[142:143]
	v_lshl_add_u64 v[248:249], v[148:149], 0, v[144:145]
	v_lshl_add_u64 v[250:251], v[148:149], 0, v[146:147]
	v_fma_f32 v236, v76, v84, v236
	v_fma_f32 v237, v77, v85, v237
	v_fma_f32 v238, v78, v86, v238
	v_fma_f32 v239, v79, v87, v239
	v_cvt_pk_bf16_f32 v236, v236, v236
	v_cvt_pk_bf16_f32 v237, v237, v237
	v_cvt_pk_bf16_f32 v238, v238, v238
	v_cvt_pk_bf16_f32 v239, v239, v239
	global_store_short v[240:241], v236, off
	global_store_short v[242:243], v237, off
	global_store_short v[248:249], v238, off
	global_store_short v[250:251], v239, off
	v_mov_b32_e32 v76, s17
	ds_read_b32 v76, v76
	v_add_u32_e32 v83, v161, v155
	v_add_u32_e32 v82, v181, v182
	v_add_u32_e32 v84, v161, v182
	v_add_u32_e32 v85, v161, v183
	v_add_u32_e32 v86, v161, v162
	ds_read_b128 v[88:91], v83 offset:34816
	ds_read_b128 v[92:95], v82 offset:34816
	ds_read_b128 v[96:99], v190 offset:34816
	ds_read_b128 v[100:103], v191 offset:34816
	ds_read_b128 v[104:107], v83 offset:44096
	ds_read_b128 v[194:197], v84 offset:46400
	ds_read_b128 v[198:201], v85 offset:48704
	ds_read_b128 v[232:235], v86 offset:51008
	s_waitcnt lgkmcnt(8)
; #define LAS __attribute__((address_space(3)))
; #define MFMA16(a, b, c) __builtin_amdgcn_mfma_f32_16x16x32_bf16((a), (b), (c), 0, 0, 0)
; template <int MODE>
; __device__ NOINL void chain_item(const LAS Params* lp, int l, int item, bool ctx_out, LAS unsigned char* lds) {
;     ...
;         {
;             const float gl = MODE == 0 ? gcs[128 + 63] : __expf(64.f * lg);
; #pragma unroll
;             for (int dk = 0; dk < NDK; ++dk) {
;                 Sacc[dk] = Sacc[dk] * gl;
; #pragma unroll
;                 for (int ks = 0; ks < 2; ++ks) { const bf16x8 A = *(const LAS bf16x8*)(KT + (kcol + 16 * dk + fr) * 72 + (((ks * 4 + fq) ^ (((kcol >> 4) + dk) & 7)) << 3)); Sacc[dk] = MFMA16(A, Bv[ks], Sacc[dk]); }
;             }
;         }
;     }
	v_pk_mul_f32 v[30:31], v[30:31], v[76:77] op_sel_hi:[1,0]
	v_pk_mul_f32 v[28:29], v[28:29], v[76:77] op_sel_hi:[1,0]
	v_pk_mul_f32 v[42:43], v[42:43], v[76:77] op_sel_hi:[1,0]
	v_pk_mul_f32 v[40:41], v[40:41], v[76:77] op_sel_hi:[1,0]
	v_pk_mul_f32 v[34:35], v[34:35], v[76:77] op_sel_hi:[1,0]
	v_pk_mul_f32 v[32:33], v[32:33], v[76:77] op_sel_hi:[1,0]
	v_pk_mul_f32 v[38:39], v[38:39], v[76:77] op_sel_hi:[1,0]
	v_pk_mul_f32 v[36:37], v[36:37], v[76:77] op_sel_hi:[1,0]
	v_pk_mul_f32 v[58:59], v[58:59], v[76:77] op_sel_hi:[1,0]
	v_pk_mul_f32 v[56:57], v[56:57], v[76:77] op_sel_hi:[1,0]
	v_pk_mul_f32 v[54:55], v[54:55], v[76:77] op_sel_hi:[1,0]
	v_pk_mul_f32 v[52:53], v[52:53], v[76:77] op_sel_hi:[1,0]
	v_pk_mul_f32 v[46:47], v[46:47], v[76:77] op_sel_hi:[1,0]
	v_pk_mul_f32 v[44:45], v[44:45], v[76:77] op_sel_hi:[1,0]
	v_pk_mul_f32 v[50:51], v[50:51], v[76:77] op_sel_hi:[1,0]
	v_pk_mul_f32 v[48:49], v[48:49], v[76:77] op_sel_hi:[1,0]
	s_waitcnt lgkmcnt(7)
	v_mfma_f32_16x16x32_bf16 v[28:31], v[88:91], v[72:75], v[28:31]
	ds_read_b128 v[88:91], v83 offset:34880
	s_waitcnt lgkmcnt(7)
	v_mfma_f32_16x16x32_bf16 v[40:43], v[92:95], v[72:75], v[40:43]
	ds_read_b128 v[92:95], v82 offset:34880
	s_waitcnt lgkmcnt(7)
	v_mfma_f32_16x16x32_bf16 v[32:35], v[96:99], v[72:75], v[32:35]
	ds_read_b128 v[96:99], v190 offset:34880
	s_waitcnt lgkmcnt(7)
	v_mfma_f32_16x16x32_bf16 v[36:39], v[100:103], v[72:75], v[36:39]
	ds_read_b128 v[100:103], v191 offset:34880
	s_waitcnt lgkmcnt(7)
	v_mfma_f32_16x16x32_bf16 v[56:59], v[104:107], v[72:75], v[56:59]
	ds_read_b128 v[104:107], v83 offset:44032
	s_waitcnt lgkmcnt(7)
	v_mfma_f32_16x16x32_bf16 v[52:55], v[194:197], v[72:75], v[52:55]
	ds_read_b128 v[194:197], v84 offset:46336
	s_waitcnt lgkmcnt(7)
	v_mfma_f32_16x16x32_bf16 v[44:47], v[198:201], v[72:75], v[44:47]
	ds_read_b128 v[198:201], v85 offset:48640
	s_waitcnt lgkmcnt(7)
	v_mfma_f32_16x16x32_bf16 v[48:51], v[232:235], v[72:75], v[48:51]
	ds_read_b128 v[232:235], v86 offset:50944
	s_waitcnt lgkmcnt(7)
	v_mfma_f32_16x16x32_bf16 v[28:31], v[88:91], v[68:71], v[28:31]
	s_waitcnt lgkmcnt(6)
	v_mfma_f32_16x16x32_bf16 v[40:43], v[92:95], v[68:71], v[40:43]
	s_waitcnt lgkmcnt(5)
	v_mfma_f32_16x16x32_bf16 v[32:35], v[96:99], v[68:71], v[32:35]
	s_waitcnt lgkmcnt(4)
	v_mfma_f32_16x16x32_bf16 v[36:39], v[100:103], v[68:71], v[36:39]
	s_waitcnt lgkmcnt(3)
	v_mfma_f32_16x16x32_bf16 v[56:59], v[104:107], v[68:71], v[56:59]
	s_waitcnt lgkmcnt(2)
	v_mfma_f32_16x16x32_bf16 v[52:55], v[194:197], v[68:71], v[52:55]
	s_waitcnt lgkmcnt(1)
	v_mfma_f32_16x16x32_bf16 v[44:47], v[198:201], v[68:71], v[44:47]
	s_waitcnt lgkmcnt(0)
	v_mfma_f32_16x16x32_bf16 v[48:51], v[232:235], v[68:71], v[48:51]
	s_waitcnt vmcnt(19)
	v_mov_b64_e32 v[74:75], v[66:67]
	v_mov_b64_e32 v[70:71], v[62:63]
	v_mov_b64_e32 v[72:73], v[64:65]
	v_mov_b64_e32 v[68:69], v[60:61]
	s_cbranch_scc0 .LBB0_1135
